# kernel start: workgroup 0 zeroes the barrier words with two dwordx4 stores per thread instead of a 7-trip dword loop
# speedup vs baseline: 1.0041x; 1.0041x over previous
; #define LAS __attribute__((address_space(3)))
; __global__ void __launch_bounds__(512) fwd_kernel(Args a) {
;     ...
;     const int tid = threadIdx.x, lane = tid & 63, wave = __builtin_amdgcn_readfirstlane(tid >> 6);
;     const int G = gridDim.x, gw = blockIdx.x * 8 + wave, NGW = G * 8;
;     cg::grid_group grid = cg::this_grid();
;     volatile LAS unsigned* xst = (volatile LAS unsigned*)(lds + LDS_BYTES - 16);
;     if (tid < 4) xst[tid] = 0u;
;     __syncthreads();
;     if (a.ph_lo == 0) { if (blockIdx.x == 0) for (int i = tid; i < XCD_BAR_WORDS; i += 512) ((unsigned*)(a.ws + WS_BAR))[i] = 0u;
;         grid.sync(); (void)xcd_barrier_post((unsigned*)(a.ws + WS_BAR), xst); }
_Z10fwd_kernel4Args:
	s_load_dwordx8 s[52:59], s[0:1], 0xa0
	s_load_dwordx8 s[60:67], s[0:1], 0x80
	s_load_dword s3, s[0:1], 0xc0
	v_and_b32_e32 v178, 0x3ff, v0
	s_add_u32 s6, s0, 0xb8
	v_readfirstlane_b32 s94, v178
	s_addc_u32 s7, s1, 0
	v_cmp_gt_u32_e32 vcc, 4, v178
	s_waitcnt lgkmcnt(0)
	v_writelane_b32 v252, s3, 0
	s_and_saveexec_b64 s[4:5], vcc
	v_lshl_add_u32 v1, v178, 2, 0
	v_add_u32_e32 v1, 0x23ff0, v1
	v_mov_b32_e32 v2, 0
	ds_write_b32 v1, v2
	s_or_b64 exec, exec, s[4:5]
	s_load_dwordx16 s[8:23], s[0:1], 0x0
	s_cmp_lg_u32 s56, 0
	s_waitcnt lgkmcnt(0)
	s_barrier
	v_writelane_b32 v252, s8, 1
	s_nop 1
	v_writelane_b32 v252, s9, 2
	v_writelane_b32 v252, s10, 3
	v_writelane_b32 v252, s11, 4
	v_writelane_b32 v252, s12, 5
	v_writelane_b32 v252, s13, 6
	v_writelane_b32 v252, s14, 7
	v_writelane_b32 v252, s15, 8
	v_writelane_b32 v252, s16, 9
	v_writelane_b32 v252, s17, 10
	v_writelane_b32 v252, s18, 11
	v_writelane_b32 v252, s19, 12
	v_writelane_b32 v252, s20, 13
	v_writelane_b32 v252, s21, 14
	v_writelane_b32 v252, s22, 15
	v_writelane_b32 v252, s23, 16
	s_cbranch_scc1 .LBB0_25
	s_cmp_lg_u32 s2, 0
	s_cbranch_scc1 .LBB0_11
	s_add_u32 s8, s54, 0x22a2000
	s_addc_u32 s9, s55, 0
	v_lshlrev_b32_e32 v1, 4, v178
	v_mov_b32_e32 v4, 0
	v_mov_b32_e32 v5, 0
	v_mov_b32_e32 v6, 0
	v_mov_b32_e32 v7, 0
	global_store_dwordx4 v1, v[4:7], s[8:9]
	v_cmp_gt_u32_e32 vcc, 0x160, v178
	s_add_u32 s10, s8, 0x2000
	s_addc_u32 s11, s9, 0
	s_and_saveexec_b64 s[12:13], vcc
	global_store_dwordx4 v1, v[4:7], s[10:11]
